# FFN-in epilogue: dropped the vmcnt(0) that only guarded the next tile's prefetch DMA (K-loop entry re-waits)
# speedup vs baseline: 1.0057x; 1.0044x over previous
.LBB0_673:
	v_add3_u32 v132, v136, v137, s52
	ds_read_b128 v[128:131], v132
	ds_read_b128 v[138:141], v132 offset:2048
	ds_read_b128 v[154:157], v132 offset:4096
	ds_read_b128 v[158:161], v132 offset:6144
	v_add3_u32 v132, v134, v137, s81
	ds_read_b128 v[162:165], v132
	ds_read_b128 v[166:169], v132 offset:2048
	ds_read_b128 v[170:173], v132 offset:4096
	ds_read_b128 v[174:177], v132 offset:6144
	ds_read_b128 v[178:181], v132 offset:8192
	ds_read_b128 v[182:185], v132 offset:10240
	ds_read_b128 v[186:189], v132 offset:12288
	ds_read_b128 v[216:219], v132 offset:14336
	s_waitcnt lgkmcnt(0)
	v_mfma_f32_16x16x32_bf16 v[116:119], v[128:131], v[162:165], v[116:119]
	v_mfma_f32_16x16x32_bf16 v[108:111], v[138:141], v[162:165], v[108:111]
	v_mfma_f32_16x16x32_bf16 v[100:103], v[154:157], v[162:165], v[100:103]
	v_mfma_f32_16x16x32_bf16 v[88:91], v[158:161], v[162:165], v[88:91]
	v_mfma_f32_16x16x32_bf16 v[76:79], v[128:131], v[166:169], v[76:79]
	v_mfma_f32_16x16x32_bf16 v[68:71], v[138:141], v[166:169], v[68:71]
	v_mfma_f32_16x16x32_bf16 v[56:59], v[154:157], v[166:169], v[56:59]
	v_mfma_f32_16x16x32_bf16 v[44:47], v[158:161], v[166:169], v[44:47]
	v_mfma_f32_16x16x32_bf16 v[36:39], v[128:131], v[170:173], v[36:39]
	v_mfma_f32_16x16x32_bf16 v[32:35], v[138:141], v[170:173], v[32:35]
	v_mfma_f32_16x16x32_bf16 v[28:31], v[154:157], v[170:173], v[28:31]
	v_mfma_f32_16x16x32_bf16 v[24:27], v[158:161], v[170:173], v[24:27]
	v_mfma_f32_16x16x32_bf16 v[20:23], v[128:131], v[174:177], v[20:23]
	v_mfma_f32_16x16x32_bf16 v[16:19], v[138:141], v[174:177], v[16:19]
	v_mfma_f32_16x16x32_bf16 v[12:15], v[154:157], v[174:177], v[12:15]
	v_mfma_f32_16x16x32_bf16 v[8:11], v[158:161], v[174:177], v[8:11]
	v_add3_u32 v132, v136, v135, s52
	v_add3_u32 v144, v134, v135, s81
	ds_read_b128 v[162:165], v132
	ds_read_b128 v[166:169], v132 offset:2048
	ds_read_b128 v[170:173], v132 offset:4096
	ds_read_b128 v[174:177], v132 offset:6144
	ds_read_b128 v[132:135], v144
	ds_read_b128 v[220:223], v144 offset:2048
	ds_read_b128 v[224:227], v144 offset:4096
	ds_read_b128 v[228:231], v144 offset:6144
	v_mfma_f32_16x16x32_bf16 v[4:7], v[128:131], v[178:181], v[4:7]
	v_mfma_f32_16x16x32_bf16 v[0:3], v[138:141], v[178:181], v[0:3]
	v_mfma_f32_16x16x32_bf16 v[40:43], v[154:157], v[178:181], v[40:43]
	v_mfma_f32_16x16x32_bf16 v[48:51], v[158:161], v[178:181], v[48:51]
	v_mfma_f32_16x16x32_bf16 v[178:181], v[128:131], v[182:185], v[52:55]
	v_mfma_f32_16x16x32_bf16 v[232:235], v[138:141], v[182:185], v[60:63]
	v_mfma_f32_16x16x32_bf16 v[236:239], v[154:157], v[182:185], v[64:67]
	v_mfma_f32_16x16x32_bf16 v[182:185], v[158:161], v[182:185], v[72:75]
	v_mfma_f32_16x16x32_bf16 v[240:243], v[128:131], v[186:189], v[80:83]
	v_mfma_f32_16x16x32_bf16 v[244:247], v[138:141], v[186:189], v[84:87]
	v_mfma_f32_16x16x32_bf16 v[248:251], v[154:157], v[186:189], v[92:95]
	v_mfma_f32_16x16x32_bf16 v[186:189], v[158:161], v[186:189], v[96:99]
	v_mfma_f32_16x16x32_bf16 v[128:131], v[128:131], v[216:219], v[104:107]
	v_mfma_f32_16x16x32_bf16 v[136:139], v[138:141], v[216:219], v[112:115]
	v_mfma_f32_16x16x32_bf16 v[140:143], v[154:157], v[216:219], v[120:123]
	v_mfma_f32_16x16x32_bf16 v[154:157], v[158:161], v[216:219], v[124:127]
	ds_read_b128 v[158:161], v144 offset:8192
	ds_read_b128 v[216:219], v144 offset:10240
	ds_read_b128 v[146:149], v144 offset:12288
	ds_read_b128 v[206:209], v144 offset:14336
	s_waitcnt lgkmcnt(0)
	v_mfma_f32_16x16x32_bf16 v[124:127], v[162:165], v[132:135], v[116:119]
	v_mfma_f32_16x16x32_bf16 v[120:123], v[166:169], v[132:135], v[108:111]
	v_mfma_f32_16x16x32_bf16 v[116:119], v[170:173], v[132:135], v[100:103]
	v_mfma_f32_16x16x32_bf16 v[112:115], v[174:177], v[132:135], v[88:91]
	v_mfma_f32_16x16x32_bf16 v[108:111], v[162:165], v[220:223], v[76:79]
	v_mfma_f32_16x16x32_bf16 v[104:107], v[166:169], v[220:223], v[68:71]
	v_mfma_f32_16x16x32_bf16 v[100:103], v[170:173], v[220:223], v[56:59]
	v_mfma_f32_16x16x32_bf16 v[96:99], v[174:177], v[220:223], v[44:47]
	v_mfma_f32_16x16x32_bf16 v[92:95], v[162:165], v[224:227], v[36:39]
	v_mfma_f32_16x16x32_bf16 v[88:91], v[166:169], v[224:227], v[32:35]
	v_mfma_f32_16x16x32_bf16 v[84:87], v[170:173], v[224:227], v[28:31]
	v_mfma_f32_16x16x32_bf16 v[80:83], v[174:177], v[224:227], v[24:27]
	v_mfma_f32_16x16x32_bf16 v[76:79], v[162:165], v[228:231], v[20:23]
	v_mfma_f32_16x16x32_bf16 v[72:75], v[166:169], v[228:231], v[16:19]
	v_mfma_f32_16x16x32_bf16 v[68:71], v[170:173], v[228:231], v[12:15]
	v_mfma_f32_16x16x32_bf16 v[64:67], v[174:177], v[228:231], v[8:11]
	v_mfma_f32_16x16x32_bf16 v[60:63], v[162:165], v[158:161], v[4:7]
	s_lshl_b32 s0, s26, 8
	s_mov_b64 s[2:3], -1
	s_and_b64 vcc, exec, s[24:25]
	v_mfma_f32_16x16x32_bf16 v[56:59], v[166:169], v[158:161], v[0:3]
	v_mfma_f32_16x16x32_bf16 v[52:55], v[170:173], v[158:161], v[40:43]
	v_mfma_f32_16x16x32_bf16 v[48:51], v[174:177], v[158:161], v[48:51]
	v_mfma_f32_16x16x32_bf16 v[44:47], v[162:165], v[216:219], v[178:181]
	v_mfma_f32_16x16x32_bf16 v[40:43], v[166:169], v[216:219], v[232:235]
	v_mfma_f32_16x16x32_bf16 v[36:39], v[170:173], v[216:219], v[236:239]
	v_mfma_f32_16x16x32_bf16 v[32:35], v[174:177], v[216:219], v[182:185]
	v_mfma_f32_16x16x32_bf16 v[28:31], v[162:165], v[146:149], v[240:243]
	v_mfma_f32_16x16x32_bf16 v[24:27], v[166:169], v[146:149], v[244:247]
	v_mfma_f32_16x16x32_bf16 v[20:23], v[170:173], v[146:149], v[248:251]
	v_mfma_f32_16x16x32_bf16 v[16:19], v[174:177], v[146:149], v[186:189]
	v_mfma_f32_16x16x32_bf16 v[12:15], v[162:165], v[206:209], v[128:131]
	v_mfma_f32_16x16x32_bf16 v[8:11], v[166:169], v[206:209], v[136:139]
	v_mfma_f32_16x16x32_bf16 v[4:7], v[170:173], v[206:209], v[140:143]
	v_mfma_f32_16x16x32_bf16 v[0:3], v[174:177], v[206:209], v[154:157]
	s_cbranch_vccz .LBB0_675
	v_mov_b32_e32 v128, v190
	s_lshl_b32 s2, s22, 7
	v_ashrrev_i32_e32 v130, 1, v128
	v_and_b32_e32 v129, 15, v128
	v_and_b32_e32 v130, 0xffffff80, v130
	v_or_b32_e32 v131, s0, v129
	v_or_b32_e32 v129, v130, v129
	v_add_u32_e32 v131, v131, v130
	v_lshl_add_u32 v130, v129, 2, v205
	ds_read_b32 v136, v130
	s_ashr_i32 s3, s2, 31
	s_lshl_b64 s[2:3], s[2:3], 1
	s_add_u32 s2, s66, s2
	s_addc_u32 s3, s67, s3
	s_waitcnt lgkmcnt(0)
	v_mul_f32_e32 v134, v124, v136
	v_mul_f32_e32 v135, 0xbfb8aa3b, v134
	v_exp_f32_e32 v135, v135
	v_lshrrev_b32_e32 v132, 1, v128
	v_and_b32_e32 v144, 0xc0, v128
	v_lshl_add_u64 v[128:129], s[2:3], 0, v[144:145]
	v_add_f32_e32 v135, 1.0, v135
	v_rcp_f32_e32 v135, v135
	v_and_b32_e32 v144, 24, v132
	v_lshl_add_u64 v[128:129], v[128:129], 0, v[144:145]
	v_and_b32_e32 v144, 8, v144
	v_mul_u32_u24_e32 v144, 3, v144
	v_lshl_add_u64 v[128:129], v[128:129], 0, v[144:145]
	v_mad_i64_i32 v[132:133], s[2:3], v131, s33, v[128:129]
	v_mul_f32_e32 v134, v134, v135
	v_mul_f32_e32 v135, v120, v136
	v_mul_f32_e32 v134, v135, v134
	v_mul_f32_e32 v135, v125, v136
	v_mul_f32_e32 v137, 0xbfb8aa3b, v135
	v_exp_f32_e32 v137, v137
	s_nop 0
	v_add_f32_e32 v137, 1.0, v137
	v_rcp_f32_e32 v137, v137
	s_nop 0
	v_mul_f32_e32 v135, v135, v137
	v_mul_f32_e32 v137, v121, v136
	v_mul_f32_e32 v135, v137, v135
	v_mul_f32_e32 v137, v126, v136
	v_mul_f32_e32 v138, 0xbfb8aa3b, v137
	v_exp_f32_e32 v138, v138
	v_cvt_pk_bf16_f32 v134, v134, v135
	s_nop 0
	v_add_f32_e32 v138, 1.0, v138
	v_rcp_f32_e32 v138, v138
	s_nop 0
	v_mul_f32_e32 v137, v137, v138
	v_mul_f32_e32 v138, v122, v136
	v_mul_f32_e32 v137, v138, v137
	v_mul_f32_e32 v138, v127, v136
	v_mul_f32_e32 v139, 0xbfb8aa3b, v138
	v_exp_f32_e32 v139, v139
	s_nop 0
	v_add_f32_e32 v139, 1.0, v139
	v_rcp_f32_e32 v139, v139
	s_nop 0
	v_mul_f32_e32 v138, v138, v139
	v_mul_f32_e32 v139, v123, v136
	v_mul_f32_e32 v138, v139, v138
	v_cvt_pk_bf16_f32 v135, v137, v138
	v_mov_b32_e32 v248, v134
	v_mov_b32_e32 v249, v135
	v_mul_f32_e32 v134, v116, v136
	v_mul_f32_e32 v135, 0xbfb8aa3b, v134
	v_exp_f32_e32 v135, v135
	s_nop 0
	v_add_f32_e32 v135, 1.0, v135
	v_rcp_f32_e32 v135, v135
	s_nop 0
	v_mul_f32_e32 v134, v134, v135
	v_mul_f32_e32 v135, v112, v136
	v_mul_f32_e32 v134, v135, v134
	v_mul_f32_e32 v135, v117, v136
	v_mul_f32_e32 v137, 0xbfb8aa3b, v135
	v_exp_f32_e32 v137, v137
	s_nop 0
	v_add_f32_e32 v137, 1.0, v137
	v_rcp_f32_e32 v137, v137
	s_nop 0
	v_mul_f32_e32 v135, v135, v137
	v_mul_f32_e32 v137, v113, v136
	v_mul_f32_e32 v135, v137, v135
	v_mul_f32_e32 v137, v118, v136
	v_mul_f32_e32 v138, 0xbfb8aa3b, v137
	v_exp_f32_e32 v138, v138
	v_cvt_pk_bf16_f32 v134, v134, v135
	s_nop 0
	v_add_f32_e32 v138, 1.0, v138
	v_rcp_f32_e32 v138, v138
	s_nop 0
	v_mul_f32_e32 v137, v137, v138
	v_mul_f32_e32 v138, v114, v136
	v_mul_f32_e32 v137, v138, v137
	v_mul_f32_e32 v138, v119, v136
	v_mul_f32_e32 v139, 0xbfb8aa3b, v138
	v_exp_f32_e32 v139, v139
	v_mul_f32_e32 v136, v115, v136
	v_add_f32_e32 v139, 1.0, v139
	v_rcp_f32_e32 v139, v139
	s_nop 0
	v_mul_f32_e32 v138, v138, v139
	v_mul_f32_e32 v136, v136, v138
	v_cvt_pk_bf16_f32 v135, v137, v136
	v_mov_b32_e32 v250, v134
	v_mov_b32_e32 v251, v135
	s_nop 1
	v_permlane16_swap_b32 v248, v250
	v_permlane16_swap_b32 v249, v251
	flat_store_dwordx4 v[132:133], v[248:251]
	ds_read_b32 v136, v130 offset:64
	v_or_b32_e32 v132, 16, v131
	v_mad_i64_i32 v[132:133], s[2:3], v132, s33, v[128:129]
	s_waitcnt lgkmcnt(0)
	v_mul_f32_e32 v134, v108, v136
	v_mul_f32_e32 v135, 0xbfb8aa3b, v134
	v_exp_f32_e32 v135, v135
	s_nop 0
	v_add_f32_e32 v135, 1.0, v135
	v_rcp_f32_e32 v135, v135
	s_nop 0
	v_mul_f32_e32 v134, v134, v135
	v_mul_f32_e32 v135, v104, v136
	v_mul_f32_e32 v134, v135, v134
	v_mul_f32_e32 v135, v109, v136
	v_mul_f32_e32 v137, 0xbfb8aa3b, v135
	v_exp_f32_e32 v137, v137
	s_nop 0
	v_add_f32_e32 v137, 1.0, v137
	v_rcp_f32_e32 v137, v137
	s_nop 0
	v_mul_f32_e32 v135, v135, v137
	v_mul_f32_e32 v137, v105, v136
	v_mul_f32_e32 v135, v137, v135
	v_mul_f32_e32 v137, v110, v136
	v_mul_f32_e32 v138, 0xbfb8aa3b, v137
	v_exp_f32_e32 v138, v138
	v_cvt_pk_bf16_f32 v134, v134, v135
	s_nop 0
	v_add_f32_e32 v138, 1.0, v138
	v_rcp_f32_e32 v138, v138
	s_nop 0
	v_mul_f32_e32 v137, v137, v138
	v_mul_f32_e32 v138, v106, v136
	v_mul_f32_e32 v137, v138, v137
	v_mul_f32_e32 v138, v111, v136
	v_mul_f32_e32 v139, 0xbfb8aa3b, v138
	v_exp_f32_e32 v139, v139
	s_nop 0
	v_add_f32_e32 v139, 1.0, v139
	v_rcp_f32_e32 v139, v139
	s_nop 0
	v_mul_f32_e32 v138, v138, v139
	v_mul_f32_e32 v139, v107, v136
	v_mul_f32_e32 v138, v139, v138
	v_cvt_pk_bf16_f32 v135, v137, v138
	v_mov_b32_e32 v248, v134
	v_mov_b32_e32 v249, v135
	v_mul_f32_e32 v134, v100, v136
	v_mul_f32_e32 v135, 0xbfb8aa3b, v134
	v_exp_f32_e32 v135, v135
	s_nop 0
	v_add_f32_e32 v135, 1.0, v135
	v_rcp_f32_e32 v135, v135
	s_nop 0
	v_mul_f32_e32 v134, v134, v135
	v_mul_f32_e32 v135, v96, v136
	v_mul_f32_e32 v134, v135, v134
	v_mul_f32_e32 v135, v101, v136
	v_mul_f32_e32 v137, 0xbfb8aa3b, v135
	v_exp_f32_e32 v137, v137
	s_nop 0
	v_add_f32_e32 v137, 1.0, v137
	v_rcp_f32_e32 v137, v137
	s_nop 0
	v_mul_f32_e32 v135, v135, v137
	v_mul_f32_e32 v137, v97, v136
	v_mul_f32_e32 v135, v137, v135
	v_mul_f32_e32 v137, v102, v136
	v_mul_f32_e32 v138, 0xbfb8aa3b, v137
	v_exp_f32_e32 v138, v138
	v_cvt_pk_bf16_f32 v134, v134, v135
	s_nop 0
	v_add_f32_e32 v138, 1.0, v138
	v_rcp_f32_e32 v138, v138
	s_nop 0
	v_mul_f32_e32 v137, v137, v138
	v_mul_f32_e32 v138, v98, v136
	v_mul_f32_e32 v137, v138, v137
	v_mul_f32_e32 v138, v103, v136
	v_mul_f32_e32 v139, 0xbfb8aa3b, v138
	v_exp_f32_e32 v139, v139
	v_mul_f32_e32 v136, v99, v136
	v_add_f32_e32 v139, 1.0, v139
	v_rcp_f32_e32 v139, v139
	s_nop 0
	v_mul_f32_e32 v138, v138, v139
	v_mul_f32_e32 v136, v136, v138
	v_cvt_pk_bf16_f32 v135, v137, v136
	v_mov_b32_e32 v250, v134
	v_mov_b32_e32 v251, v135
	s_nop 1
	v_permlane16_swap_b32 v248, v250
	v_permlane16_swap_b32 v249, v251
	flat_store_dwordx4 v[132:133], v[248:251]
	ds_read_b32 v136, v130 offset:128
	v_or_b32_e32 v132, 32, v131
	v_mad_i64_i32 v[132:133], s[2:3], v132, s33, v[128:129]
	s_waitcnt lgkmcnt(0)
	v_mul_f32_e32 v134, v92, v136
	v_mul_f32_e32 v135, 0xbfb8aa3b, v134
	v_exp_f32_e32 v135, v135
	s_nop 0
	v_add_f32_e32 v135, 1.0, v135
	v_rcp_f32_e32 v135, v135
	s_nop 0
	v_mul_f32_e32 v134, v134, v135
	v_mul_f32_e32 v135, v88, v136
	v_mul_f32_e32 v134, v135, v134
	v_mul_f32_e32 v135, v93, v136
	v_mul_f32_e32 v137, 0xbfb8aa3b, v135
	v_exp_f32_e32 v137, v137
	s_nop 0
	v_add_f32_e32 v137, 1.0, v137
	v_rcp_f32_e32 v137, v137
	s_nop 0
	v_mul_f32_e32 v135, v135, v137
	v_mul_f32_e32 v137, v89, v136
	v_mul_f32_e32 v135, v137, v135
	v_mul_f32_e32 v137, v94, v136
	v_mul_f32_e32 v138, 0xbfb8aa3b, v137
	v_exp_f32_e32 v138, v138
	v_cvt_pk_bf16_f32 v134, v134, v135
	s_nop 0
	v_add_f32_e32 v138, 1.0, v138
	v_rcp_f32_e32 v138, v138
	s_nop 0
	v_mul_f32_e32 v137, v137, v138
	v_mul_f32_e32 v138, v90, v136
	v_mul_f32_e32 v137, v138, v137
	v_mul_f32_e32 v138, v95, v136
	v_mul_f32_e32 v139, 0xbfb8aa3b, v138
	v_exp_f32_e32 v139, v139
	s_nop 0
	v_add_f32_e32 v139, 1.0, v139
	v_rcp_f32_e32 v139, v139
	s_nop 0
	v_mul_f32_e32 v138, v138, v139
	v_mul_f32_e32 v139, v91, v136
	v_mul_f32_e32 v138, v139, v138
	v_cvt_pk_bf16_f32 v135, v137, v138
	v_mov_b32_e32 v248, v134
	v_mov_b32_e32 v249, v135
	v_mul_f32_e32 v134, v84, v136
	v_mul_f32_e32 v135, 0xbfb8aa3b, v134
	v_exp_f32_e32 v135, v135
	s_nop 0
	v_add_f32_e32 v135, 1.0, v135
	v_rcp_f32_e32 v135, v135
	s_nop 0
	v_mul_f32_e32 v134, v134, v135
	v_mul_f32_e32 v135, v80, v136
	v_mul_f32_e32 v134, v135, v134
	v_mul_f32_e32 v135, v85, v136
	v_mul_f32_e32 v137, 0xbfb8aa3b, v135
	v_exp_f32_e32 v137, v137
	s_nop 0
	v_add_f32_e32 v137, 1.0, v137
	v_rcp_f32_e32 v137, v137
	s_nop 0
	v_mul_f32_e32 v135, v135, v137
	v_mul_f32_e32 v137, v81, v136
	v_mul_f32_e32 v135, v137, v135
	v_mul_f32_e32 v137, v86, v136
	v_mul_f32_e32 v138, 0xbfb8aa3b, v137
	v_exp_f32_e32 v138, v138
	v_cvt_pk_bf16_f32 v134, v134, v135
	s_nop 0
	v_add_f32_e32 v138, 1.0, v138
	v_rcp_f32_e32 v138, v138
	s_nop 0
	v_mul_f32_e32 v137, v137, v138
	v_mul_f32_e32 v138, v82, v136
	v_mul_f32_e32 v137, v138, v137
	v_mul_f32_e32 v138, v87, v136
	v_mul_f32_e32 v139, 0xbfb8aa3b, v138
	v_exp_f32_e32 v139, v139
	v_mul_f32_e32 v136, v83, v136
	v_add_f32_e32 v139, 1.0, v139
	v_rcp_f32_e32 v139, v139
	s_nop 0
	v_mul_f32_e32 v138, v138, v139
	v_mul_f32_e32 v136, v136, v138
	v_cvt_pk_bf16_f32 v135, v137, v136
	v_mov_b32_e32 v250, v134
	v_mov_b32_e32 v251, v135
	s_nop 1
	v_permlane16_swap_b32 v248, v250
	v_permlane16_swap_b32 v249, v251
	flat_store_dwordx4 v[132:133], v[248:251]
	ds_read_b32 v136, v130 offset:192
	v_or_b32_e32 v132, 48, v131
	v_mad_i64_i32 v[132:133], s[2:3], v132, s33, v[128:129]
	s_waitcnt lgkmcnt(0)
	v_mul_f32_e32 v134, v76, v136
	v_mul_f32_e32 v135, 0xbfb8aa3b, v134
	v_exp_f32_e32 v135, v135
	s_nop 0
	v_add_f32_e32 v135, 1.0, v135
	v_rcp_f32_e32 v135, v135
	s_nop 0
	v_mul_f32_e32 v134, v134, v135
	v_mul_f32_e32 v135, v72, v136
	v_mul_f32_e32 v134, v135, v134
	v_mul_f32_e32 v135, v77, v136
	v_mul_f32_e32 v137, 0xbfb8aa3b, v135
	v_exp_f32_e32 v137, v137
	s_nop 0
	v_add_f32_e32 v137, 1.0, v137
	v_rcp_f32_e32 v137, v137
	s_nop 0
	v_mul_f32_e32 v135, v135, v137
	v_mul_f32_e32 v137, v73, v136
	v_mul_f32_e32 v135, v137, v135
	v_mul_f32_e32 v137, v78, v136
	v_mul_f32_e32 v138, 0xbfb8aa3b, v137
	v_exp_f32_e32 v138, v138
	v_cvt_pk_bf16_f32 v134, v134, v135
	s_nop 0
	v_add_f32_e32 v138, 1.0, v138
	v_rcp_f32_e32 v138, v138
	s_nop 0
	v_mul_f32_e32 v137, v137, v138
	v_mul_f32_e32 v138, v74, v136
	v_mul_f32_e32 v137, v138, v137
	v_mul_f32_e32 v138, v79, v136
	v_mul_f32_e32 v139, 0xbfb8aa3b, v138
	v_exp_f32_e32 v139, v139
	s_nop 0
	v_add_f32_e32 v139, 1.0, v139
	v_rcp_f32_e32 v139, v139
	s_nop 0
	v_mul_f32_e32 v138, v138, v139
	v_mul_f32_e32 v139, v75, v136
	v_mul_f32_e32 v138, v139, v138
	v_cvt_pk_bf16_f32 v135, v137, v138
	v_mov_b32_e32 v248, v134
	v_mov_b32_e32 v249, v135
	v_mul_f32_e32 v134, v68, v136
	v_mul_f32_e32 v135, 0xbfb8aa3b, v134
	v_exp_f32_e32 v135, v135
	s_nop 0
	v_add_f32_e32 v135, 1.0, v135
	v_rcp_f32_e32 v135, v135
	s_nop 0
	v_mul_f32_e32 v134, v134, v135
	v_mul_f32_e32 v135, v64, v136
	v_mul_f32_e32 v134, v135, v134
	v_mul_f32_e32 v135, v69, v136
	v_mul_f32_e32 v137, 0xbfb8aa3b, v135
	v_exp_f32_e32 v137, v137
	s_nop 0
	v_add_f32_e32 v137, 1.0, v137
	v_rcp_f32_e32 v137, v137
	s_nop 0
	v_mul_f32_e32 v135, v135, v137
	v_mul_f32_e32 v137, v65, v136
	v_mul_f32_e32 v135, v137, v135
	v_mul_f32_e32 v137, v70, v136
	v_mul_f32_e32 v138, 0xbfb8aa3b, v137
	v_exp_f32_e32 v138, v138
	v_cvt_pk_bf16_f32 v134, v134, v135
	s_nop 0
	v_add_f32_e32 v138, 1.0, v138
	v_rcp_f32_e32 v138, v138
	s_nop 0
	v_mul_f32_e32 v137, v137, v138
	v_mul_f32_e32 v138, v66, v136
	v_mul_f32_e32 v137, v138, v137
	v_mul_f32_e32 v138, v71, v136
	v_mul_f32_e32 v139, 0xbfb8aa3b, v138
	v_exp_f32_e32 v139, v139
	v_mul_f32_e32 v136, v67, v136
	v_add_f32_e32 v139, 1.0, v139
	v_rcp_f32_e32 v139, v139
	s_nop 0
	v_mul_f32_e32 v138, v138, v139
	v_mul_f32_e32 v136, v136, v138
	v_cvt_pk_bf16_f32 v135, v137, v136
	v_mov_b32_e32 v250, v134
	v_mov_b32_e32 v251, v135
	s_nop 1
	v_permlane16_swap_b32 v248, v250
	v_permlane16_swap_b32 v249, v251
	flat_store_dwordx4 v[132:133], v[248:251]
	ds_read_b32 v136, v130 offset:256
	v_or_b32_e32 v132, 64, v131
	v_mad_i64_i32 v[132:133], s[2:3], v132, s33, v[128:129]
	s_waitcnt lgkmcnt(0)
	v_mul_f32_e32 v134, v60, v136
	v_mul_f32_e32 v135, 0xbfb8aa3b, v134
	v_exp_f32_e32 v135, v135
	s_nop 0
	v_add_f32_e32 v135, 1.0, v135
	v_rcp_f32_e32 v135, v135
	s_nop 0
	v_mul_f32_e32 v134, v134, v135
	v_mul_f32_e32 v135, v56, v136
	v_mul_f32_e32 v134, v135, v134
	v_mul_f32_e32 v135, v61, v136
	v_mul_f32_e32 v137, 0xbfb8aa3b, v135
	v_exp_f32_e32 v137, v137
	s_nop 0
	v_add_f32_e32 v137, 1.0, v137
	v_rcp_f32_e32 v137, v137
	s_nop 0
	v_mul_f32_e32 v135, v135, v137
	v_mul_f32_e32 v137, v57, v136
	v_mul_f32_e32 v135, v137, v135
	v_mul_f32_e32 v137, v62, v136
	v_mul_f32_e32 v138, 0xbfb8aa3b, v137
	v_exp_f32_e32 v138, v138
	v_cvt_pk_bf16_f32 v134, v134, v135
	s_nop 0
	v_add_f32_e32 v138, 1.0, v138
	v_rcp_f32_e32 v138, v138
	s_nop 0
	v_mul_f32_e32 v137, v137, v138
	v_mul_f32_e32 v138, v58, v136
	v_mul_f32_e32 v137, v138, v137
	v_mul_f32_e32 v138, v63, v136
	v_mul_f32_e32 v139, 0xbfb8aa3b, v138
	v_exp_f32_e32 v139, v139
	s_nop 0
	v_add_f32_e32 v139, 1.0, v139
	v_rcp_f32_e32 v139, v139
	s_nop 0
	v_mul_f32_e32 v138, v138, v139
	v_mul_f32_e32 v139, v59, v136
	v_mul_f32_e32 v138, v139, v138
	v_cvt_pk_bf16_f32 v135, v137, v138
	v_mov_b32_e32 v248, v134
	v_mov_b32_e32 v249, v135
	v_mul_f32_e32 v134, v52, v136
	v_mul_f32_e32 v135, 0xbfb8aa3b, v134
	v_exp_f32_e32 v135, v135
	s_nop 0
	v_add_f32_e32 v135, 1.0, v135
	v_rcp_f32_e32 v135, v135
	s_nop 0
	v_mul_f32_e32 v134, v134, v135
	v_mul_f32_e32 v135, v48, v136
	v_mul_f32_e32 v134, v135, v134
	v_mul_f32_e32 v135, v53, v136
	v_mul_f32_e32 v137, 0xbfb8aa3b, v135
	v_exp_f32_e32 v137, v137
	s_nop 0
	v_add_f32_e32 v137, 1.0, v137
	v_rcp_f32_e32 v137, v137
	s_nop 0
	v_mul_f32_e32 v135, v135, v137
	v_mul_f32_e32 v137, v49, v136
	v_mul_f32_e32 v135, v137, v135
	v_mul_f32_e32 v137, v54, v136
	v_mul_f32_e32 v138, 0xbfb8aa3b, v137
	v_exp_f32_e32 v138, v138
	v_cvt_pk_bf16_f32 v134, v134, v135
	s_nop 0
	v_add_f32_e32 v138, 1.0, v138
	v_rcp_f32_e32 v138, v138
	s_nop 0
	v_mul_f32_e32 v137, v137, v138
	v_mul_f32_e32 v138, v50, v136
	v_mul_f32_e32 v137, v138, v137
	v_mul_f32_e32 v138, v55, v136
	v_mul_f32_e32 v139, 0xbfb8aa3b, v138
	v_exp_f32_e32 v139, v139
	v_mul_f32_e32 v136, v51, v136
	v_add_f32_e32 v139, 1.0, v139
	v_rcp_f32_e32 v139, v139
	s_nop 0
	v_mul_f32_e32 v138, v138, v139
	v_mul_f32_e32 v136, v136, v138
	v_cvt_pk_bf16_f32 v135, v137, v136
	v_mov_b32_e32 v250, v134
	v_mov_b32_e32 v251, v135
	s_nop 1
	v_permlane16_swap_b32 v248, v250
	v_permlane16_swap_b32 v249, v251
	flat_store_dwordx4 v[132:133], v[248:251]
	ds_read_b32 v136, v130 offset:320
	v_or_b32_e32 v132, 0x50, v131
	v_mad_i64_i32 v[132:133], s[2:3], v132, s33, v[128:129]
	s_waitcnt lgkmcnt(0)
	v_mul_f32_e32 v134, v44, v136
	v_mul_f32_e32 v135, 0xbfb8aa3b, v134
	v_exp_f32_e32 v135, v135
	s_nop 0
	v_add_f32_e32 v135, 1.0, v135
	v_rcp_f32_e32 v135, v135
	s_nop 0
	v_mul_f32_e32 v134, v134, v135
	v_mul_f32_e32 v135, v40, v136
	v_mul_f32_e32 v134, v135, v134
	v_mul_f32_e32 v135, v45, v136
	v_mul_f32_e32 v137, 0xbfb8aa3b, v135
	v_exp_f32_e32 v137, v137
	s_nop 0
	v_add_f32_e32 v137, 1.0, v137
	v_rcp_f32_e32 v137, v137
	s_nop 0
	v_mul_f32_e32 v135, v135, v137
	v_mul_f32_e32 v137, v41, v136
	v_mul_f32_e32 v135, v137, v135
	v_mul_f32_e32 v137, v46, v136
	v_mul_f32_e32 v138, 0xbfb8aa3b, v137
	v_exp_f32_e32 v138, v138
	v_cvt_pk_bf16_f32 v134, v134, v135
	s_nop 0
	v_add_f32_e32 v138, 1.0, v138
	v_rcp_f32_e32 v138, v138
	s_nop 0
	v_mul_f32_e32 v137, v137, v138
	v_mul_f32_e32 v138, v42, v136
	v_mul_f32_e32 v137, v138, v137
	v_mul_f32_e32 v138, v47, v136
	v_mul_f32_e32 v139, 0xbfb8aa3b, v138
	v_exp_f32_e32 v139, v139
	s_nop 0
	v_add_f32_e32 v139, 1.0, v139
	v_rcp_f32_e32 v139, v139
	s_nop 0
	v_mul_f32_e32 v138, v138, v139
	v_mul_f32_e32 v139, v43, v136
	v_mul_f32_e32 v138, v139, v138
	v_cvt_pk_bf16_f32 v135, v137, v138
	v_mov_b32_e32 v248, v134
	v_mov_b32_e32 v249, v135
	v_mul_f32_e32 v134, v36, v136
	v_mul_f32_e32 v135, 0xbfb8aa3b, v134
	v_exp_f32_e32 v135, v135
	s_nop 0
	v_add_f32_e32 v135, 1.0, v135
	v_rcp_f32_e32 v135, v135
	s_nop 0
	v_mul_f32_e32 v134, v134, v135
	v_mul_f32_e32 v135, v32, v136
	v_mul_f32_e32 v134, v135, v134
	v_mul_f32_e32 v135, v37, v136
	v_mul_f32_e32 v137, 0xbfb8aa3b, v135
	v_exp_f32_e32 v137, v137
	s_nop 0
	v_add_f32_e32 v137, 1.0, v137
	v_rcp_f32_e32 v137, v137
	s_nop 0
	v_mul_f32_e32 v135, v135, v137
	v_mul_f32_e32 v137, v33, v136
	v_mul_f32_e32 v135, v137, v135
	v_mul_f32_e32 v137, v38, v136
	v_mul_f32_e32 v138, 0xbfb8aa3b, v137
	v_exp_f32_e32 v138, v138
	v_cvt_pk_bf16_f32 v134, v134, v135
	s_nop 0
	v_add_f32_e32 v138, 1.0, v138
	v_rcp_f32_e32 v138, v138
	s_nop 0
	v_mul_f32_e32 v137, v137, v138
	v_mul_f32_e32 v138, v34, v136
	v_mul_f32_e32 v137, v138, v137
	v_mul_f32_e32 v138, v39, v136
	v_mul_f32_e32 v139, 0xbfb8aa3b, v138
	v_exp_f32_e32 v139, v139
	v_mul_f32_e32 v136, v35, v136
	v_add_f32_e32 v139, 1.0, v139
	v_rcp_f32_e32 v139, v139
	s_nop 0
	v_mul_f32_e32 v138, v138, v139
	v_mul_f32_e32 v136, v136, v138
	v_cvt_pk_bf16_f32 v135, v137, v136
	v_mov_b32_e32 v250, v134
	v_mov_b32_e32 v251, v135
	s_nop 1
	v_permlane16_swap_b32 v248, v250
	v_permlane16_swap_b32 v249, v251
	flat_store_dwordx4 v[132:133], v[248:251]
	ds_read_b32 v136, v130 offset:384
	v_or_b32_e32 v132, 0x60, v131
	v_mad_i64_i32 v[132:133], s[2:3], v132, s33, v[128:129]
	v_or_b32_e32 v131, 0x70, v131
	s_waitcnt lgkmcnt(0)
	v_mul_f32_e32 v134, v28, v136
	v_mul_f32_e32 v135, 0xbfb8aa3b, v134
	v_exp_f32_e32 v135, v135
	v_mad_i64_i32 v[128:129], s[2:3], v131, s33, v[128:129]
	v_add_f32_e32 v135, 1.0, v135
	v_rcp_f32_e32 v135, v135
	s_nop 0
	v_mul_f32_e32 v134, v134, v135
	v_mul_f32_e32 v135, v24, v136
	v_mul_f32_e32 v134, v135, v134
	v_mul_f32_e32 v135, v29, v136
	v_mul_f32_e32 v137, 0xbfb8aa3b, v135
	v_exp_f32_e32 v137, v137
	s_nop 0
	v_add_f32_e32 v137, 1.0, v137
	v_rcp_f32_e32 v137, v137
	s_nop 0
	v_mul_f32_e32 v135, v135, v137
	v_mul_f32_e32 v137, v25, v136
	v_mul_f32_e32 v135, v137, v135
	v_mul_f32_e32 v137, v30, v136
	v_mul_f32_e32 v138, 0xbfb8aa3b, v137
	v_exp_f32_e32 v138, v138
	v_cvt_pk_bf16_f32 v134, v134, v135
	s_nop 0
	v_add_f32_e32 v138, 1.0, v138
	v_rcp_f32_e32 v138, v138
	s_nop 0
	v_mul_f32_e32 v137, v137, v138
	v_mul_f32_e32 v138, v26, v136
	v_mul_f32_e32 v137, v138, v137
	v_mul_f32_e32 v138, v31, v136
	v_mul_f32_e32 v139, 0xbfb8aa3b, v138
	v_exp_f32_e32 v139, v139
	s_nop 0
	v_add_f32_e32 v139, 1.0, v139
	v_rcp_f32_e32 v139, v139
	s_nop 0
	v_mul_f32_e32 v138, v138, v139
	v_mul_f32_e32 v139, v27, v136
	v_mul_f32_e32 v138, v139, v138
	v_cvt_pk_bf16_f32 v135, v137, v138
	v_mov_b32_e32 v248, v134
	v_mov_b32_e32 v249, v135
	v_mul_f32_e32 v134, v20, v136
	v_mul_f32_e32 v135, 0xbfb8aa3b, v134
	v_exp_f32_e32 v135, v135
	s_nop 0
	v_add_f32_e32 v135, 1.0, v135
	v_rcp_f32_e32 v135, v135
	s_nop 0
	v_mul_f32_e32 v134, v134, v135
	v_mul_f32_e32 v135, v16, v136
	v_mul_f32_e32 v134, v135, v134
	v_mul_f32_e32 v135, v21, v136
	v_mul_f32_e32 v137, 0xbfb8aa3b, v135
	v_exp_f32_e32 v137, v137
	s_nop 0
	v_add_f32_e32 v137, 1.0, v137
	v_rcp_f32_e32 v137, v137
	s_nop 0
	v_mul_f32_e32 v135, v135, v137
	v_mul_f32_e32 v137, v17, v136
	v_mul_f32_e32 v135, v137, v135
	v_mul_f32_e32 v137, v22, v136
	v_mul_f32_e32 v138, 0xbfb8aa3b, v137
	v_exp_f32_e32 v138, v138
	v_cvt_pk_bf16_f32 v134, v134, v135
	s_nop 0
	v_add_f32_e32 v138, 1.0, v138
	v_rcp_f32_e32 v138, v138
	s_nop 0
	v_mul_f32_e32 v137, v137, v138
	v_mul_f32_e32 v138, v18, v136
	v_mul_f32_e32 v137, v138, v137
	v_mul_f32_e32 v138, v23, v136
	v_mul_f32_e32 v139, 0xbfb8aa3b, v138
	v_exp_f32_e32 v139, v139
	v_mul_f32_e32 v136, v19, v136
	v_add_f32_e32 v139, 1.0, v139
	v_rcp_f32_e32 v139, v139
	s_nop 0
	v_mul_f32_e32 v138, v138, v139
	v_mul_f32_e32 v136, v136, v138
	v_cvt_pk_bf16_f32 v135, v137, v136
	v_mov_b32_e32 v250, v134
	v_mov_b32_e32 v251, v135
	s_nop 1
	v_permlane16_swap_b32 v248, v250
	v_permlane16_swap_b32 v249, v251
	flat_store_dwordx4 v[132:133], v[248:251]
	ds_read_b32 v132, v130 offset:448
	s_waitcnt lgkmcnt(0)
	v_mul_f32_e32 v130, v12, v132
	v_mul_f32_e32 v131, 0xbfb8aa3b, v130
	v_exp_f32_e32 v131, v131
	s_nop 0
	v_add_f32_e32 v131, 1.0, v131
	v_rcp_f32_e32 v131, v131
	s_nop 0
	v_mul_f32_e32 v130, v130, v131
	v_mul_f32_e32 v131, v8, v132
	v_mul_f32_e32 v130, v131, v130
	v_mul_f32_e32 v131, v13, v132
	v_mul_f32_e32 v133, 0xbfb8aa3b, v131
	v_exp_f32_e32 v133, v133
	s_nop 0
	v_add_f32_e32 v133, 1.0, v133
	v_rcp_f32_e32 v133, v133
	s_nop 0
	v_mul_f32_e32 v131, v131, v133
	v_mul_f32_e32 v133, v9, v132
	v_mul_f32_e32 v131, v133, v131
	v_mul_f32_e32 v133, v14, v132
	v_mul_f32_e32 v134, 0xbfb8aa3b, v133
	v_exp_f32_e32 v134, v134
	v_cvt_pk_bf16_f32 v130, v130, v131
	s_nop 0
	v_add_f32_e32 v134, 1.0, v134
	v_rcp_f32_e32 v134, v134
	s_nop 0
	v_mul_f32_e32 v133, v133, v134
	v_mul_f32_e32 v134, v10, v132
	v_mul_f32_e32 v133, v134, v133
	v_mul_f32_e32 v134, v15, v132
	v_mul_f32_e32 v135, 0xbfb8aa3b, v134
	v_exp_f32_e32 v135, v135
	s_nop 0
	v_add_f32_e32 v135, 1.0, v135
	v_rcp_f32_e32 v135, v135
	s_nop 0
	v_mul_f32_e32 v134, v134, v135
	v_mul_f32_e32 v135, v11, v132
	v_mul_f32_e32 v134, v135, v134
	v_cvt_pk_bf16_f32 v131, v133, v134
	v_mov_b32_e32 v248, v130
	v_mov_b32_e32 v249, v131
	v_mul_f32_e32 v130, v4, v132
	v_mul_f32_e32 v131, 0xbfb8aa3b, v130
	v_exp_f32_e32 v131, v131
	s_nop 0
	v_add_f32_e32 v131, 1.0, v131
	v_rcp_f32_e32 v131, v131
	s_nop 0
	v_mul_f32_e32 v130, v130, v131
	v_mul_f32_e32 v131, v0, v132
	v_mul_f32_e32 v130, v131, v130
	v_mul_f32_e32 v131, v5, v132
	v_mul_f32_e32 v133, 0xbfb8aa3b, v131
	v_exp_f32_e32 v133, v133
	s_nop 0
	v_add_f32_e32 v133, 1.0, v133
	v_rcp_f32_e32 v133, v133
	s_nop 0
	v_mul_f32_e32 v131, v131, v133
	v_mul_f32_e32 v133, v1, v132
	v_mul_f32_e32 v131, v133, v131
	v_mul_f32_e32 v133, v6, v132
	v_mul_f32_e32 v134, 0xbfb8aa3b, v133
	v_exp_f32_e32 v134, v134
	v_cvt_pk_bf16_f32 v130, v130, v131
	s_nop 0
	v_add_f32_e32 v134, 1.0, v134
	v_rcp_f32_e32 v134, v134
	s_nop 0
	v_mul_f32_e32 v133, v133, v134
	v_mul_f32_e32 v134, v2, v132
	v_mul_f32_e32 v133, v134, v133
	v_mul_f32_e32 v134, v7, v132
	v_mul_f32_e32 v135, 0xbfb8aa3b, v134
	v_exp_f32_e32 v135, v135
	v_mul_f32_e32 v132, v3, v132
	v_add_f32_e32 v135, 1.0, v135
	v_rcp_f32_e32 v135, v135
	s_nop 0
	v_mul_f32_e32 v134, v134, v135
	v_mul_f32_e32 v132, v132, v134
	v_cvt_pk_bf16_f32 v131, v133, v132
	v_mov_b32_e32 v250, v130
	v_mov_b32_e32 v251, v131
	s_nop 1
	v_permlane16_swap_b32 v248, v250
	v_permlane16_swap_b32 v249, v251
	flat_store_dwordx4 v[128:129], v[248:251]
	s_cbranch_execnz .LBB0_653
	s_branch .LBB0_676
